# P4 attn_sample P V loop hand-pipelined: 32 V loads in flight instead of one exposed round trip per three keys
# speedup vs baseline: 1.0261x; 1.0080x over previous
.LBB0_561:
	s_and_b32 s56, s86, 7
	s_ashr_i32 s63, s62, 31
	s_lshl_b32 s64, s56, 8
	s_lshl_b64 s[62:63], s[62:63], 20
	s_or_b32 s62, s62, s64
	s_lshl_b32 s56, s56, 7
	v_lshl_add_u64 v[2:3], v[74:75], 0, s[62:63]
	s_mul_i32 s62, s88, 0x2c00
	s_mul_hi_i32 s63, s88, 0x2c00
	s_or_b32 s62, s62, s56
	v_mov_b32_e32 v0, 0
	v_lshl_add_u64 v[4:5], v[76:77], 0, s[62:63]
	s_mov_b32 s56, 0
	s_mov_b64 s[62:63], 0
	v_mov_b32_e32 v7, v88
	v_mov_b32_e32 v13, v87
	v_mov_b32_e32 v1, v0
	s_waitcnt lgkmcnt(0)
	s_barrier
	s_mov_b32 s62, 0x1000
	s_mov_b32 s63, 0
	global_load_dword v16, v[2:3], off
	global_load_dword v17, v[2:3], off offset:2048
	v_lshl_add_u64 v[2:3], v[2:3], 0, s[62:63]
	global_load_dword v18, v[2:3], off
	global_load_dword v19, v[2:3], off offset:2048
	v_lshl_add_u64 v[2:3], v[2:3], 0, s[62:63]
	global_load_dword v20, v[2:3], off
	global_load_dword v21, v[2:3], off offset:2048
	v_lshl_add_u64 v[2:3], v[2:3], 0, s[62:63]
	global_load_dword v22, v[2:3], off
	global_load_dword v23, v[2:3], off offset:2048
	v_lshl_add_u64 v[2:3], v[2:3], 0, s[62:63]
	global_load_dword v24, v[2:3], off
	global_load_dword v25, v[2:3], off offset:2048
	v_lshl_add_u64 v[2:3], v[2:3], 0, s[62:63]
	global_load_dword v26, v[2:3], off
	global_load_dword v27, v[2:3], off offset:2048
	v_lshl_add_u64 v[2:3], v[2:3], 0, s[62:63]
	global_load_dword v28, v[2:3], off
	global_load_dword v29, v[2:3], off offset:2048
	v_lshl_add_u64 v[2:3], v[2:3], 0, s[62:63]
	global_load_dword v30, v[2:3], off
	global_load_dword v31, v[2:3], off offset:2048
	v_lshl_add_u64 v[2:3], v[2:3], 0, s[62:63]
	global_load_dword v32, v[2:3], off
	global_load_dword v33, v[2:3], off offset:2048
	v_lshl_add_u64 v[2:3], v[2:3], 0, s[62:63]
	global_load_dword v34, v[2:3], off
	global_load_dword v35, v[2:3], off offset:2048
	v_lshl_add_u64 v[2:3], v[2:3], 0, s[62:63]
	global_load_dword v36, v[2:3], off
	global_load_dword v37, v[2:3], off offset:2048
	v_lshl_add_u64 v[2:3], v[2:3], 0, s[62:63]
	global_load_dword v38, v[2:3], off
	global_load_dword v39, v[2:3], off offset:2048
	v_lshl_add_u64 v[2:3], v[2:3], 0, s[62:63]
	global_load_dword v40, v[2:3], off
	global_load_dword v41, v[2:3], off offset:2048
	v_lshl_add_u64 v[2:3], v[2:3], 0, s[62:63]
	global_load_dword v42, v[2:3], off
	global_load_dword v43, v[2:3], off offset:2048
	v_lshl_add_u64 v[2:3], v[2:3], 0, s[62:63]
	global_load_dword v44, v[2:3], off
	global_load_dword v45, v[2:3], off offset:2048
	v_lshl_add_u64 v[2:3], v[2:3], 0, s[62:63]
	global_load_dword v46, v[2:3], off
	global_load_dword v47, v[2:3], off offset:2048
	v_lshl_add_u64 v[2:3], v[2:3], 0, s[62:63]
	s_mov_b32 s56, 15
.Lasv_loop:
	ds_read_b128 v[48:51], v7
	ds_read_b128 v[112:115], v13
	ds_read_b128 v[52:55], v7 offset:16
	ds_read_b128 v[116:119], v13 offset:16
	ds_read_b128 v[56:59], v7 offset:32
	ds_read_b128 v[120:123], v13 offset:32
	ds_read_b128 v[60:63], v7 offset:48
	ds_read_b128 v[124:127], v13 offset:48
	s_waitcnt lgkmcnt(6)
	s_waitcnt vmcnt(31)
	v_fma_f32 v0, v16, v112, v0
	v_fma_f32 v1, v16, v48, v1
	s_waitcnt vmcnt(30)
	v_fma_f32 v0, v17, v113, v0
	v_fma_f32 v1, v17, v49, v1
	s_waitcnt vmcnt(29)
	v_fma_f32 v0, v18, v114, v0
	v_fma_f32 v1, v18, v50, v1
	s_waitcnt vmcnt(28)
	v_fma_f32 v0, v19, v115, v0
	v_fma_f32 v1, v19, v51, v1
	s_waitcnt lgkmcnt(4)
	s_waitcnt vmcnt(27)
	v_fma_f32 v0, v20, v116, v0
	v_fma_f32 v1, v20, v52, v1
	s_waitcnt vmcnt(26)
	v_fma_f32 v0, v21, v117, v0
	v_fma_f32 v1, v21, v53, v1
	s_waitcnt vmcnt(25)
	v_fma_f32 v0, v22, v118, v0
	v_fma_f32 v1, v22, v54, v1
	s_waitcnt vmcnt(24)
	v_fma_f32 v0, v23, v119, v0
	v_fma_f32 v1, v23, v55, v1
	s_waitcnt lgkmcnt(2)
	s_waitcnt vmcnt(23)
	v_fma_f32 v0, v24, v120, v0
	v_fma_f32 v1, v24, v56, v1
	s_waitcnt vmcnt(22)
	v_fma_f32 v0, v25, v121, v0
	v_fma_f32 v1, v25, v57, v1
	s_waitcnt vmcnt(21)
	v_fma_f32 v0, v26, v122, v0
	v_fma_f32 v1, v26, v58, v1
	s_waitcnt vmcnt(20)
	v_fma_f32 v0, v27, v123, v0
	v_fma_f32 v1, v27, v59, v1
	s_waitcnt lgkmcnt(0)
	s_waitcnt vmcnt(19)
	v_fma_f32 v0, v28, v124, v0
	v_fma_f32 v1, v28, v60, v1
	s_waitcnt vmcnt(18)
	v_fma_f32 v0, v29, v125, v0
	v_fma_f32 v1, v29, v61, v1
	s_waitcnt vmcnt(17)
	v_fma_f32 v0, v30, v126, v0
	v_fma_f32 v1, v30, v62, v1
	s_waitcnt vmcnt(16)
	v_fma_f32 v0, v31, v127, v0
	v_fma_f32 v1, v31, v63, v1
	global_load_dword v16, v[2:3], off
	global_load_dword v17, v[2:3], off offset:2048
	v_lshl_add_u64 v[2:3], v[2:3], 0, s[62:63]
	global_load_dword v18, v[2:3], off
	global_load_dword v19, v[2:3], off offset:2048
	v_lshl_add_u64 v[2:3], v[2:3], 0, s[62:63]
	global_load_dword v20, v[2:3], off
	global_load_dword v21, v[2:3], off offset:2048
	v_lshl_add_u64 v[2:3], v[2:3], 0, s[62:63]
	global_load_dword v22, v[2:3], off
	global_load_dword v23, v[2:3], off offset:2048
	v_lshl_add_u64 v[2:3], v[2:3], 0, s[62:63]
	global_load_dword v24, v[2:3], off
	global_load_dword v25, v[2:3], off offset:2048
	v_lshl_add_u64 v[2:3], v[2:3], 0, s[62:63]
	global_load_dword v26, v[2:3], off
	global_load_dword v27, v[2:3], off offset:2048
	v_lshl_add_u64 v[2:3], v[2:3], 0, s[62:63]
	global_load_dword v28, v[2:3], off
	global_load_dword v29, v[2:3], off offset:2048
	v_lshl_add_u64 v[2:3], v[2:3], 0, s[62:63]
	global_load_dword v30, v[2:3], off
	global_load_dword v31, v[2:3], off offset:2048
	v_lshl_add_u64 v[2:3], v[2:3], 0, s[62:63]
	ds_read_b128 v[96:99], v7 offset:64
	ds_read_b128 v[128:131], v13 offset:64
	ds_read_b128 v[100:103], v7 offset:80
	ds_read_b128 v[132:135], v13 offset:80
	ds_read_b128 v[104:107], v7 offset:96
	ds_read_b128 v[136:139], v13 offset:96
	ds_read_b128 v[108:111], v7 offset:112
	ds_read_b128 v[140:143], v13 offset:112
	s_waitcnt lgkmcnt(6)
	s_waitcnt vmcnt(31)
	v_fma_f32 v0, v32, v128, v0
	v_fma_f32 v1, v32, v96, v1
	s_waitcnt vmcnt(30)
	v_fma_f32 v0, v33, v129, v0
	v_fma_f32 v1, v33, v97, v1
	s_waitcnt vmcnt(29)
	v_fma_f32 v0, v34, v130, v0
	v_fma_f32 v1, v34, v98, v1
	s_waitcnt vmcnt(28)
	v_fma_f32 v0, v35, v131, v0
	v_fma_f32 v1, v35, v99, v1
	s_waitcnt lgkmcnt(4)
	s_waitcnt vmcnt(27)
	v_fma_f32 v0, v36, v132, v0
	v_fma_f32 v1, v36, v100, v1
	s_waitcnt vmcnt(26)
	v_fma_f32 v0, v37, v133, v0
	v_fma_f32 v1, v37, v101, v1
	s_waitcnt vmcnt(25)
	v_fma_f32 v0, v38, v134, v0
	v_fma_f32 v1, v38, v102, v1
	s_waitcnt vmcnt(24)
	v_fma_f32 v0, v39, v135, v0
	v_fma_f32 v1, v39, v103, v1
	s_waitcnt lgkmcnt(2)
	s_waitcnt vmcnt(23)
	v_fma_f32 v0, v40, v136, v0
	v_fma_f32 v1, v40, v104, v1
	s_waitcnt vmcnt(22)
	v_fma_f32 v0, v41, v137, v0
	v_fma_f32 v1, v41, v105, v1
	s_waitcnt vmcnt(21)
	v_fma_f32 v0, v42, v138, v0
	v_fma_f32 v1, v42, v106, v1
	s_waitcnt vmcnt(20)
	v_fma_f32 v0, v43, v139, v0
	v_fma_f32 v1, v43, v107, v1
	s_waitcnt lgkmcnt(0)
	s_waitcnt vmcnt(19)
	v_fma_f32 v0, v44, v140, v0
	v_fma_f32 v1, v44, v108, v1
	s_waitcnt vmcnt(18)
	v_fma_f32 v0, v45, v141, v0
	v_fma_f32 v1, v45, v109, v1
	s_waitcnt vmcnt(17)
	v_fma_f32 v0, v46, v142, v0
	v_fma_f32 v1, v46, v110, v1
	s_waitcnt vmcnt(16)
	v_fma_f32 v0, v47, v143, v0
	v_fma_f32 v1, v47, v111, v1
	global_load_dword v32, v[2:3], off
	global_load_dword v33, v[2:3], off offset:2048
	v_lshl_add_u64 v[2:3], v[2:3], 0, s[62:63]
	global_load_dword v34, v[2:3], off
	global_load_dword v35, v[2:3], off offset:2048
	v_lshl_add_u64 v[2:3], v[2:3], 0, s[62:63]
	global_load_dword v36, v[2:3], off
	global_load_dword v37, v[2:3], off offset:2048
	v_lshl_add_u64 v[2:3], v[2:3], 0, s[62:63]
	global_load_dword v38, v[2:3], off
	global_load_dword v39, v[2:3], off offset:2048
	v_lshl_add_u64 v[2:3], v[2:3], 0, s[62:63]
	global_load_dword v40, v[2:3], off
	global_load_dword v41, v[2:3], off offset:2048
	v_lshl_add_u64 v[2:3], v[2:3], 0, s[62:63]
	global_load_dword v42, v[2:3], off
	global_load_dword v43, v[2:3], off offset:2048
	v_lshl_add_u64 v[2:3], v[2:3], 0, s[62:63]
	global_load_dword v44, v[2:3], off
	global_load_dword v45, v[2:3], off offset:2048
	v_lshl_add_u64 v[2:3], v[2:3], 0, s[62:63]
	global_load_dword v46, v[2:3], off
	global_load_dword v47, v[2:3], off offset:2048
	v_lshl_add_u64 v[2:3], v[2:3], 0, s[62:63]
	v_add_u32_e32 v7, 0x80, v7
	v_add_u32_e32 v13, 0x80, v13
	s_sub_u32 s56, s56, 1
	s_cmp_lg_u32 s56, 0
	s_cbranch_scc1 .Lasv_loop
	s_mov_b32 s62, 0x3df00800
	s_mov_b32 s63, 0
	v_lshl_add_u64 v[10:11], v[4:5], 0, s[62:63]
	s_mov_b32 s62, 0x2c00
	global_load_ushort v144, v[10:11], off
	v_lshl_add_u64 v[10:11], v[10:11], 0, s[62:63]
	global_load_ushort v145, v[10:11], off
	v_lshl_add_u64 v[10:11], v[10:11], 0, s[62:63]
	global_load_ushort v146, v[10:11], off
	v_lshl_add_u64 v[10:11], v[10:11], 0, s[62:63]
	global_load_ushort v147, v[10:11], off
	v_lshl_add_u64 v[10:11], v[10:11], 0, s[62:63]
	global_load_ushort v148, v[10:11], off
	v_lshl_add_u64 v[10:11], v[10:11], 0, s[62:63]
	global_load_ushort v149, v[10:11], off
	v_lshl_add_u64 v[10:11], v[10:11], 0, s[62:63]
	global_load_ushort v150, v[10:11], off
	v_lshl_add_u64 v[10:11], v[10:11], 0, s[62:63]
	global_load_ushort v151, v[10:11], off
	v_lshl_add_u64 v[10:11], v[10:11], 0, s[62:63]
	global_load_ushort v152, v[10:11], off
	v_lshl_add_u64 v[10:11], v[10:11], 0, s[62:63]
	global_load_ushort v153, v[10:11], off
	v_lshl_add_u64 v[10:11], v[10:11], 0, s[62:63]
	global_load_ushort v154, v[10:11], off
	v_lshl_add_u64 v[10:11], v[10:11], 0, s[62:63]
	global_load_ushort v155, v[10:11], off
	v_lshl_add_u64 v[10:11], v[10:11], 0, s[62:63]
	global_load_ushort v156, v[10:11], off
	v_lshl_add_u64 v[10:11], v[10:11], 0, s[62:63]
	global_load_ushort v157, v[10:11], off
	v_lshl_add_u64 v[10:11], v[10:11], 0, s[62:63]
	global_load_ushort v158, v[10:11], off
	v_lshl_add_u64 v[10:11], v[10:11], 0, s[62:63]
	global_load_ushort v159, v[10:11], off
	ds_read_b128 v[48:51], v7
	ds_read_b128 v[112:115], v13
	ds_read_b128 v[52:55], v7 offset:16
	ds_read_b128 v[116:119], v13 offset:16
	ds_read_b128 v[56:59], v7 offset:32
	ds_read_b128 v[120:123], v13 offset:32
	ds_read_b128 v[60:63], v7 offset:48
	ds_read_b128 v[124:127], v13 offset:48
	s_waitcnt lgkmcnt(6)
	s_waitcnt vmcnt(47)
	v_fma_f32 v0, v16, v112, v0
	v_fma_f32 v1, v16, v48, v1
	s_waitcnt vmcnt(46)
	v_fma_f32 v0, v17, v113, v0
	v_fma_f32 v1, v17, v49, v1
	s_waitcnt vmcnt(45)
	v_fma_f32 v0, v18, v114, v0
	v_fma_f32 v1, v18, v50, v1
	s_waitcnt vmcnt(44)
	v_fma_f32 v0, v19, v115, v0
	v_fma_f32 v1, v19, v51, v1
	s_waitcnt lgkmcnt(4)
	s_waitcnt vmcnt(43)
	v_fma_f32 v0, v20, v116, v0
	v_fma_f32 v1, v20, v52, v1
	s_waitcnt vmcnt(42)
	v_fma_f32 v0, v21, v117, v0
	v_fma_f32 v1, v21, v53, v1
	s_waitcnt vmcnt(41)
	v_fma_f32 v0, v22, v118, v0
	v_fma_f32 v1, v22, v54, v1
	s_waitcnt vmcnt(40)
	v_fma_f32 v0, v23, v119, v0
	v_fma_f32 v1, v23, v55, v1
	s_waitcnt lgkmcnt(2)
	s_waitcnt vmcnt(39)
	v_fma_f32 v0, v24, v120, v0
	v_fma_f32 v1, v24, v56, v1
	s_waitcnt vmcnt(38)
	v_fma_f32 v0, v25, v121, v0
	v_fma_f32 v1, v25, v57, v1
	s_waitcnt vmcnt(37)
	v_fma_f32 v0, v26, v122, v0
	v_fma_f32 v1, v26, v58, v1
	s_waitcnt vmcnt(36)
	v_fma_f32 v0, v27, v123, v0
	v_fma_f32 v1, v27, v59, v1
	s_waitcnt lgkmcnt(0)
	s_waitcnt vmcnt(35)
	v_fma_f32 v0, v28, v124, v0
	v_fma_f32 v1, v28, v60, v1
	s_waitcnt vmcnt(34)
	v_fma_f32 v0, v29, v125, v0
	v_fma_f32 v1, v29, v61, v1
	s_waitcnt vmcnt(33)
	v_fma_f32 v0, v30, v126, v0
	v_fma_f32 v1, v30, v62, v1
	s_waitcnt vmcnt(32)
	v_fma_f32 v0, v31, v127, v0
	v_fma_f32 v1, v31, v63, v1
	ds_read_b128 v[96:99], v7 offset:64
	ds_read_b128 v[128:131], v13 offset:64
	ds_read_b128 v[100:103], v7 offset:80
	ds_read_b128 v[132:135], v13 offset:80
	ds_read_b128 v[104:107], v7 offset:96
	ds_read_b128 v[136:139], v13 offset:96
	ds_read_b128 v[108:111], v7 offset:112
	ds_read_b128 v[140:143], v13 offset:112
	s_waitcnt lgkmcnt(6)
	s_waitcnt vmcnt(31)
	v_fma_f32 v0, v32, v128, v0
	v_fma_f32 v1, v32, v96, v1
	s_waitcnt vmcnt(30)
	v_fma_f32 v0, v33, v129, v0
	v_fma_f32 v1, v33, v97, v1
	s_waitcnt vmcnt(29)
	v_fma_f32 v0, v34, v130, v0
	v_fma_f32 v1, v34, v98, v1
	s_waitcnt vmcnt(28)
	v_fma_f32 v0, v35, v131, v0
	v_fma_f32 v1, v35, v99, v1
	s_waitcnt lgkmcnt(4)
	s_waitcnt vmcnt(27)
	v_fma_f32 v0, v36, v132, v0
	v_fma_f32 v1, v36, v100, v1
	s_waitcnt vmcnt(26)
	v_fma_f32 v0, v37, v133, v0
	v_fma_f32 v1, v37, v101, v1
	s_waitcnt vmcnt(25)
	v_fma_f32 v0, v38, v134, v0
	v_fma_f32 v1, v38, v102, v1
	s_waitcnt vmcnt(24)
	v_fma_f32 v0, v39, v135, v0
	v_fma_f32 v1, v39, v103, v1
	s_waitcnt lgkmcnt(2)
	s_waitcnt vmcnt(23)
	v_fma_f32 v0, v40, v136, v0
	v_fma_f32 v1, v40, v104, v1
	s_waitcnt vmcnt(22)
	v_fma_f32 v0, v41, v137, v0
	v_fma_f32 v1, v41, v105, v1
	s_waitcnt vmcnt(21)
	v_fma_f32 v0, v42, v138, v0
	v_fma_f32 v1, v42, v106, v1
	s_waitcnt vmcnt(20)
	v_fma_f32 v0, v43, v139, v0
	v_fma_f32 v1, v43, v107, v1
	s_waitcnt lgkmcnt(0)
	s_waitcnt vmcnt(19)
	v_fma_f32 v0, v44, v140, v0
	v_fma_f32 v1, v44, v108, v1
	s_waitcnt vmcnt(18)
	v_fma_f32 v0, v45, v141, v0
	v_fma_f32 v1, v45, v109, v1
	s_waitcnt vmcnt(17)
	v_fma_f32 v0, v46, v142, v0
	v_fma_f32 v1, v46, v110, v1
	s_waitcnt vmcnt(16)
	v_fma_f32 v0, v47, v143, v0
	v_fma_f32 v1, v47, v111, v1
	ds_read_b128 v[48:51], v7 offset:128
	ds_read_b128 v[112:115], v13 offset:128
	ds_read_b128 v[52:55], v7 offset:144
	ds_read_b128 v[116:119], v13 offset:144
	ds_read_b128 v[56:59], v7 offset:160
	ds_read_b128 v[120:123], v13 offset:160
	ds_read_b128 v[60:63], v7 offset:176
	ds_read_b128 v[124:127], v13 offset:176
	s_waitcnt lgkmcnt(6)
	s_waitcnt vmcnt(15)
	v_lshlrev_b32_e32 v144, 16, v144
	v_fma_f32 v0, v144, v112, v0
	v_fma_f32 v1, v144, v48, v1
	s_waitcnt vmcnt(14)
	v_lshlrev_b32_e32 v145, 16, v145
	v_fma_f32 v0, v145, v113, v0
	v_fma_f32 v1, v145, v49, v1
	s_waitcnt vmcnt(13)
	v_lshlrev_b32_e32 v146, 16, v146
	v_fma_f32 v0, v146, v114, v0
	v_fma_f32 v1, v146, v50, v1
	s_waitcnt vmcnt(12)
	v_lshlrev_b32_e32 v147, 16, v147
	v_fma_f32 v0, v147, v115, v0
	v_fma_f32 v1, v147, v51, v1
	s_waitcnt lgkmcnt(4)
	s_waitcnt vmcnt(11)
	v_lshlrev_b32_e32 v148, 16, v148
	v_fma_f32 v0, v148, v116, v0
	v_fma_f32 v1, v148, v52, v1
	s_waitcnt vmcnt(10)
	v_lshlrev_b32_e32 v149, 16, v149
	v_fma_f32 v0, v149, v117, v0
	v_fma_f32 v1, v149, v53, v1
	s_waitcnt vmcnt(9)
	v_lshlrev_b32_e32 v150, 16, v150
	v_fma_f32 v0, v150, v118, v0
	v_fma_f32 v1, v150, v54, v1
	s_waitcnt vmcnt(8)
	v_lshlrev_b32_e32 v151, 16, v151
	v_fma_f32 v0, v151, v119, v0
	v_fma_f32 v1, v151, v55, v1
	s_waitcnt lgkmcnt(2)
	s_waitcnt vmcnt(7)
	v_lshlrev_b32_e32 v152, 16, v152
	v_fma_f32 v0, v152, v120, v0
	v_fma_f32 v1, v152, v56, v1
	s_waitcnt vmcnt(6)
	v_lshlrev_b32_e32 v153, 16, v153
	v_fma_f32 v0, v153, v121, v0
	v_fma_f32 v1, v153, v57, v1
	s_waitcnt vmcnt(5)
	v_lshlrev_b32_e32 v154, 16, v154
	v_fma_f32 v0, v154, v122, v0
	v_fma_f32 v1, v154, v58, v1
	s_waitcnt vmcnt(4)
	v_lshlrev_b32_e32 v155, 16, v155
	v_fma_f32 v0, v155, v123, v0
	v_fma_f32 v1, v155, v59, v1
	s_waitcnt lgkmcnt(0)
	s_waitcnt vmcnt(3)
	v_lshlrev_b32_e32 v156, 16, v156
	v_fma_f32 v0, v156, v124, v0
	v_fma_f32 v1, v156, v60, v1
	s_waitcnt vmcnt(2)
	v_lshlrev_b32_e32 v157, 16, v157
	v_fma_f32 v0, v157, v125, v0
	v_fma_f32 v1, v157, v61, v1
	s_waitcnt vmcnt(1)
	v_lshlrev_b32_e32 v158, 16, v158
	v_fma_f32 v0, v158, v126, v0
	v_fma_f32 v1, v158, v62, v1
	s_waitcnt vmcnt(0)
	v_lshlrev_b32_e32 v159, 16, v159
	v_fma_f32 v0, v159, v127, v0
	v_fma_f32 v1, v159, v63, v1
	s_waitcnt vmcnt(0)
	s_branch .LBB0_528
